# P3 chain rewrite + fused diff-attention loop + gla_out norm-gain load hoisted (no vmcnt(0) stall) + second diff unit reuses gain tables already in LDS
# speedup vs baseline: 1.0091x; 1.0049x over previous
; #define LAS __attribute__((address_space(3)))
; __device__ __forceinline__ float frcp(float x) { return __builtin_amdgcn_rcpf(x); }
; __device__ __forceinline__ int crow(int r, int hi) { return (r & 3) + 8 * (r >> 2) + 4 * hi; }
; template <bool BG = false>
; __device__ __forceinline__ void diff_unit(Frame& F, int bh, int c, BgConv* bg = nullptr) {
;     ...
;     const float lam = sc[0];
;     if (tid < 256) ((LAS float*)(lds + AT_G + 1024))[tid] = F.in[14][tid] * (1.0f - LAM_INIT);
; #pragma unroll
;     for (int i = 0; i < 16; ++i) { const int q = crow(i, h);
;         const float l1 = lbuf[((0 * 2 + rbB) * 2 + 0) * 32 + q] + lbuf[((0 * 2 + rbB) * 2 + 1) * 32 + q];
;         const float l2 = lbuf[((1 * 2 + rbB) * 2 + 0) * 32 + q] + lbuf[((1 * 2 + rbB) * 2 + 1) * 32 + q];
;         const float i1 = frcp(l1), i2 = lam * frcp(l2);
;         LAS unsigned char* orow = lds + (32 * rbB + q) * 1024; const int sw = (q & 1) << 4;
;         *(LAS float*)(orow + (((64 * dvp + r) * 4) ^ sw)) = O[0][0][i] * i1 - O[1][0][i] * i2;
;         *(LAS float*)(orow + (((64 * dvp + 32 + r) * 4) ^ sw)) = O[0][1][i] * i1 - O[1][1][i] * i2; }
.LBB0_751:
	s_or_b64 exec, exec, s[36:37]
	v_lshrrev_b32_e32 v69, 3, v68
	v_and_b32_e32 v69, 4, v69
	v_lshl_add_u32 v70, v69, 2, s13
	ds_read_b32 v71, v70 offset:512
	ds_read_b32 v72, v70 offset:640
	ds_read_b32 v73, v70
	ds_read_b32 v74, v70 offset:128
	v_and_or_b32 v75, v68, 31, s33
	v_lshl_add_u32 v69, v69, 10, s15
	s_waitcnt lgkmcnt(2)
	v_add_f32_e32 v71, v71, v72
	v_rcp_f32_e32 v71, v71
	s_waitcnt lgkmcnt(0)
	v_add_f32_e32 v73, v73, v74
	v_rcp_f32_e32 v73, v73
	v_lshlrev_b32_e32 v72, 2, v75
	s_waitcnt vmcnt(0)
	v_mul_f32_e32 v71, v2, v71
	v_mul_f32_e32 v20, v20, v71
	v_mul_f32_e32 v4, v4, v71
	v_fma_f32 v20, v52, v73, -v20
	v_add_u32_e32 v52, v69, v72
	v_fma_f32 v4, v36, v73, -v4
	ds_write2_b32 v52, v20, v4 offset1:32
	ds_read_b32 v4, v70 offset:516
	ds_read_b32 v20, v70 offset:644
	ds_read_b32 v36, v70 offset:4
	ds_read_b32 v71, v70 offset:132
	s_waitcnt lgkmcnt(2)
	v_add_f32_e32 v4, v4, v20
	v_rcp_f32_e32 v4, v4
	s_waitcnt lgkmcnt(0)
	v_add_f32_e32 v20, v36, v71
	v_rcp_f32_e32 v20, v20
	v_xad_u32 v36, v72, 16, v69
	v_mul_f32_e32 v4, v2, v4
	v_mul_f32_e32 v21, v21, v4
	v_mul_f32_e32 v4, v5, v4
	v_fma_f32 v21, v53, v20, -v21
	v_fma_f32 v4, v37, v20, -v4
	v_add_u32_e32 v5, 0x400, v36
	ds_write2_b32 v5, v21, v4 offset1:32
	ds_read_b32 v4, v70 offset:520
	ds_read_b32 v5, v70 offset:648
	ds_read_b32 v20, v70 offset:8
	ds_read_b32 v21, v70 offset:136
	s_waitcnt lgkmcnt(2)
	v_add_f32_e32 v4, v4, v5
	v_rcp_f32_e32 v4, v4
	s_waitcnt lgkmcnt(0)
	v_add_f32_e32 v5, v20, v21
	v_rcp_f32_e32 v5, v5
	v_mul_f32_e32 v4, v2, v4
	v_mul_f32_e32 v20, v22, v4
	v_mul_f32_e32 v4, v6, v4
	v_fma_f32 v20, v54, v5, -v20
	v_fma_f32 v4, v38, v5, -v4
	v_add_u32_e32 v5, 0x800, v52
	ds_write2_b32 v5, v20, v4 offset1:32
	ds_read_b32 v4, v70 offset:524
	ds_read_b32 v5, v70 offset:652
	ds_read_b32 v6, v70 offset:12
	ds_read_b32 v20, v70 offset:140
	s_waitcnt lgkmcnt(2)
	v_add_f32_e32 v4, v4, v5
	v_rcp_f32_e32 v4, v4
	s_waitcnt lgkmcnt(0)
	v_add_f32_e32 v5, v6, v20
	v_rcp_f32_e32 v5, v5
	v_mul_f32_e32 v4, v2, v4
	v_mul_f32_e32 v6, v23, v4
	v_mul_f32_e32 v4, v7, v4
	v_fma_f32 v6, v55, v5, -v6
	v_fma_f32 v4, v39, v5, -v4
	v_add_u32_e32 v5, 0xc00, v36
	ds_write2_b32 v5, v6, v4 offset1:32
	ds_read_b32 v4, v70 offset:544
	ds_read_b32 v5, v70 offset:672
	ds_read_b32 v6, v70 offset:32
	ds_read_b32 v7, v70 offset:160
	s_waitcnt lgkmcnt(2)
	v_add_f32_e32 v4, v4, v5
	v_rcp_f32_e32 v4, v4
	s_waitcnt lgkmcnt(0)
	v_add_f32_e32 v5, v6, v7
	v_rcp_f32_e32 v5, v5
	v_mul_f32_e32 v4, v2, v4
	v_mul_f32_e32 v6, v24, v4
	v_mul_f32_e32 v4, v8, v4
	v_fma_f32 v6, v56, v5, -v6
	v_fma_f32 v4, v40, v5, -v4
	v_add_u32_e32 v5, 0x2000, v52
	ds_write2_b32 v5, v6, v4 offset1:32
	ds_read_b32 v4, v70 offset:548
	ds_read_b32 v5, v70 offset:676
	ds_read_b32 v6, v70 offset:36
	ds_read_b32 v7, v70 offset:164
	s_waitcnt lgkmcnt(2)
	v_add_f32_e32 v4, v4, v5
	v_rcp_f32_e32 v4, v4
	s_waitcnt lgkmcnt(0)
	v_add_f32_e32 v5, v6, v7
	v_rcp_f32_e32 v5, v5
	v_mul_f32_e32 v4, v2, v4
	v_mul_f32_e32 v6, v25, v4
	v_mul_f32_e32 v4, v9, v4
	v_fma_f32 v6, v57, v5, -v6
	v_fma_f32 v4, v41, v5, -v4
	v_add_u32_e32 v5, 0x2400, v36
	ds_write2_b32 v5, v6, v4 offset1:32
	ds_read_b32 v4, v70 offset:552
	ds_read_b32 v5, v70 offset:680
	ds_read_b32 v6, v70 offset:40
	ds_read_b32 v7, v70 offset:168
	s_waitcnt lgkmcnt(2)
	v_add_f32_e32 v4, v4, v5
	v_rcp_f32_e32 v4, v4
	s_waitcnt lgkmcnt(0)
	v_add_f32_e32 v5, v6, v7
	v_rcp_f32_e32 v5, v5
	v_mul_f32_e32 v4, v2, v4
	v_mul_f32_e32 v6, v26, v4
	v_mul_f32_e32 v4, v10, v4
	v_fma_f32 v6, v58, v5, -v6
	v_fma_f32 v4, v42, v5, -v4
	v_add_u32_e32 v5, 0x2800, v52
	ds_write2_b32 v5, v6, v4 offset1:32
	ds_read_b32 v4, v70 offset:556
	ds_read_b32 v5, v70 offset:684
	ds_read_b32 v6, v70 offset:44
	ds_read_b32 v7, v70 offset:172
	s_waitcnt lgkmcnt(2)
	v_add_f32_e32 v4, v4, v5
	v_rcp_f32_e32 v4, v4
	s_waitcnt lgkmcnt(0)
	v_add_f32_e32 v5, v6, v7
	v_rcp_f32_e32 v5, v5
	v_mul_f32_e32 v4, v2, v4
	v_mul_f32_e32 v6, v27, v4
	v_mul_f32_e32 v4, v11, v4
	v_fma_f32 v6, v59, v5, -v6
	v_fma_f32 v4, v43, v5, -v4
	v_add_u32_e32 v5, 0x2c00, v36
	ds_write2_b32 v5, v6, v4 offset1:32
	ds_read_b32 v4, v70 offset:576
	ds_read_b32 v5, v70 offset:704
	ds_read_b32 v6, v70 offset:64
	ds_read_b32 v7, v70 offset:192
	s_waitcnt lgkmcnt(2)
	v_add_f32_e32 v4, v4, v5
	v_rcp_f32_e32 v4, v4
	s_waitcnt lgkmcnt(0)
	v_add_f32_e32 v5, v6, v7
	v_rcp_f32_e32 v5, v5
	v_mul_f32_e32 v4, v2, v4
	v_mul_f32_e32 v6, v28, v4
	v_mul_f32_e32 v4, v12, v4
	v_fma_f32 v6, v60, v5, -v6
	v_fma_f32 v4, v44, v5, -v4
	v_add_u32_e32 v5, 0x4000, v52
	ds_write2_b32 v5, v6, v4 offset1:32
	ds_read_b32 v4, v70 offset:580
	ds_read_b32 v5, v70 offset:708
	ds_read_b32 v6, v70 offset:68
	ds_read_b32 v7, v70 offset:196
	s_waitcnt lgkmcnt(2)
	v_add_f32_e32 v4, v4, v5
	v_rcp_f32_e32 v4, v4
	s_waitcnt lgkmcnt(0)
	v_add_f32_e32 v5, v6, v7
	v_rcp_f32_e32 v5, v5
	v_mul_f32_e32 v4, v2, v4
	v_mul_f32_e32 v6, v29, v4
	v_mul_f32_e32 v4, v13, v4
	v_fma_f32 v6, v61, v5, -v6
	v_fma_f32 v4, v45, v5, -v4
	v_add_u32_e32 v5, 0x4400, v36
	ds_write2_b32 v5, v6, v4 offset1:32
	ds_read_b32 v4, v70 offset:584
	ds_read_b32 v5, v70 offset:712
	ds_read_b32 v6, v70 offset:72
	ds_read_b32 v7, v70 offset:200
	s_waitcnt lgkmcnt(2)
	v_add_f32_e32 v4, v4, v5
	v_rcp_f32_e32 v4, v4
	s_waitcnt lgkmcnt(0)
	v_add_f32_e32 v5, v6, v7
	v_rcp_f32_e32 v5, v5
	v_mul_f32_e32 v4, v2, v4
	v_mul_f32_e32 v6, v30, v4
	v_mul_f32_e32 v4, v14, v4
	v_fma_f32 v6, v62, v5, -v6
	v_fma_f32 v4, v46, v5, -v4
	v_add_u32_e32 v5, 0x4800, v52
	ds_write2_b32 v5, v6, v4 offset1:32
	ds_read_b32 v4, v70 offset:588
	ds_read_b32 v5, v70 offset:716
	ds_read_b32 v6, v70 offset:76
	ds_read_b32 v7, v70 offset:204
	s_waitcnt lgkmcnt(2)
; #define LAS __attribute__((address_space(3)))
; __device__ __forceinline__ float frcp(float x) { return __builtin_amdgcn_rcpf(x); }
; __device__ __forceinline__ float frsq(float x) { return __builtin_amdgcn_rsqf(x); }
; __device__ __forceinline__ int crow(int r, int hi) { return (r & 3) + 8 * (r >> 2) + 4 * hi; }
; template <bool BG = false>
; __device__ __forceinline__ void diff_unit(Frame& F, int bh, int c, BgConv* bg = nullptr) {
;     ...
;     for (int i = 0; i < 16; ++i) { const int q = crow(i, h);
;         const float l1 = lbuf[((0 * 2 + rbB) * 2 + 0) * 32 + q] + lbuf[((0 * 2 + rbB) * 2 + 1) * 32 + q];
;         const float l2 = lbuf[((1 * 2 + rbB) * 2 + 0) * 32 + q] + lbuf[((1 * 2 + rbB) * 2 + 1) * 32 + q];
;         const float i1 = frcp(l1), i2 = lam * frcp(l2);
;         LAS unsigned char* orow = lds + (32 * rbB + q) * 1024; const int sw = (q & 1) << 4;
;         *(LAS float*)(orow + (((64 * dvp + r) * 4) ^ sw)) = O[0][0][i] * i1 - O[1][0][i] * i2;
;         *(LAS float*)(orow + (((64 * dvp + 32 + r) * 4) ^ sw)) = O[0][1][i] * i1 - O[1][1][i] * i2; }
;     __syncthreads();
;     { const int l = tid >> 3, sw = (l & 1) << 4;
;       const LAS unsigned char* orow = lds + l * 1024;
;       const LAS f32x4* gnt = (const LAS f32x4*)(lds + AT_G + 1024);
;       f32x4 o[4][2]; float ss = 0.f;
; #pragma unroll
;       for (int i = 0; i < 4; ++i) { const int ch = (tid & 7) + 8 * i;
;           o[i][0] = *(const LAS f32x4*)(orow + ((ch * 32) ^ sw)); o[i][1] = *(const LAS f32x4*)(orow + ((ch * 32 + 16) ^ sw));
; #pragma unroll
;           for (int e = 0; e < 4; ++e) ss += o[i][0][e] * o[i][0][e] + o[i][1][e] * o[i][1][e]; }
;       ss += __shfl_xor(ss, 1); ss += __shfl_xor(ss, 2); ss += __shfl_xor(ss, 4);
;       const float rn = frsq(ss * (1.0f / 256.0f) + NORM_EPS);
	v_add_f32_e32 v4, v4, v5
	v_rcp_f32_e32 v4, v4
	s_waitcnt lgkmcnt(0)
	v_add_f32_e32 v5, v6, v7
	v_rcp_f32_e32 v5, v5
	v_mul_f32_e32 v4, v2, v4
	v_mul_f32_e32 v6, v31, v4
	v_mul_f32_e32 v4, v15, v4
	v_fma_f32 v6, v63, v5, -v6
	v_fma_f32 v4, v47, v5, -v4
	v_add_u32_e32 v5, 0x4c00, v36
	ds_write2_b32 v5, v6, v4 offset1:32
	ds_read_b32 v4, v70 offset:608
	ds_read_b32 v5, v70 offset:736
	ds_read_b32 v6, v70 offset:96
	ds_read_b32 v7, v70 offset:224
	s_waitcnt lgkmcnt(2)
	v_add_f32_e32 v4, v4, v5
	v_rcp_f32_e32 v4, v4
	s_waitcnt lgkmcnt(0)
	v_add_f32_e32 v5, v6, v7
	v_rcp_f32_e32 v5, v5
	v_mul_f32_e32 v4, v2, v4
	v_mul_f32_e32 v6, v32, v4
	v_mul_f32_e32 v4, v16, v4
	v_fma_f32 v6, v64, v5, -v6
	v_fma_f32 v4, v48, v5, -v4
	v_add_u32_e32 v5, 0x6000, v52
	ds_write2_b32 v5, v6, v4 offset1:32
	ds_read_b32 v4, v70 offset:612
	ds_read_b32 v5, v70 offset:740
	ds_read_b32 v6, v70 offset:100
	ds_read_b32 v7, v70 offset:228
	s_waitcnt lgkmcnt(2)
	v_add_f32_e32 v4, v4, v5
	v_rcp_f32_e32 v4, v4
	s_waitcnt lgkmcnt(0)
	v_add_f32_e32 v5, v6, v7
	v_rcp_f32_e32 v5, v5
	v_mul_f32_e32 v4, v2, v4
	v_mul_f32_e32 v6, v33, v4
	v_mul_f32_e32 v4, v17, v4
	v_fma_f32 v6, v65, v5, -v6
	v_fma_f32 v4, v49, v5, -v4
	v_add_u32_e32 v5, 0x6400, v36
	ds_write2_b32 v5, v6, v4 offset1:32
	ds_read_b32 v4, v70 offset:616
	ds_read_b32 v5, v70 offset:744
	ds_read_b32 v6, v70 offset:104
	ds_read_b32 v7, v70 offset:232
	s_waitcnt lgkmcnt(2)
	v_add_f32_e32 v4, v4, v5
	v_rcp_f32_e32 v4, v4
	s_waitcnt lgkmcnt(0)
	v_add_f32_e32 v5, v6, v7
	v_rcp_f32_e32 v5, v5
	v_mul_f32_e32 v4, v2, v4
	v_mul_f32_e32 v6, v34, v4
	v_mul_f32_e32 v4, v18, v4
	v_fma_f32 v6, v66, v5, -v6
	v_fma_f32 v4, v50, v5, -v4
	v_add_u32_e32 v5, 0x6800, v52
	ds_write2_b32 v5, v6, v4 offset1:32
	ds_read_b32 v4, v70 offset:620
	ds_read_b32 v5, v70 offset:748
	ds_read_b32 v6, v70 offset:108
	ds_read_b32 v7, v70 offset:236
	s_waitcnt lgkmcnt(2)
	v_add_f32_e32 v4, v4, v5
	v_rcp_f32_e32 v4, v4
	s_waitcnt lgkmcnt(0)
	v_add_f32_e32 v5, v6, v7
	v_rcp_f32_e32 v5, v5
	v_mul_f32_e32 v2, v2, v4
	v_mul_f32_e32 v4, v35, v2
	v_mul_f32_e32 v2, v19, v2
	v_fma_f32 v4, v67, v5, -v4
	v_fma_f32 v2, v51, v5, -v2
	v_add_u32_e32 v5, 0x6c00, v36
	ds_write2_b32 v5, v4, v2 offset1:32
	v_ashrrev_i32_e32 v2, 3, v68
	v_lshlrev_b32_e32 v4, 4, v2
	v_and_b32_e32 v28, 16, v4
	v_lshlrev_b32_e32 v4, 5, v68
	v_and_b32_e32 v30, 0xe0, v4
	v_lshl_add_u32 v29, v2, 10, 0
	v_or_b32_e32 v4, 16, v30
	v_xad_u32 v4, v4, v28, v29
	s_waitcnt lgkmcnt(0)
	s_barrier
	v_add3_u32 v32, v29, v28, v30
	ds_read_b128 v[4:7], v4
	ds_read_b128 v[8:11], v32
	v_or_b32_e32 v12, 0x110, v30
	v_xad_u32 v12, v12, v28, v29
	ds_read_b128 v[12:15], v12
	ds_read_b128 v[16:19], v32 offset:256
	s_waitcnt lgkmcnt(3)
	v_mul_f32_e32 v20, v4, v4
	v_mul_f32_e32 v21, v5, v5
	s_waitcnt lgkmcnt(2)
	v_fmac_f32_e32 v20, v8, v8
	v_fmac_f32_e32 v21, v9, v9
	v_add_f32_e32 v20, v20, v21
	v_mul_f32_e32 v21, v6, v6
	v_fmac_f32_e32 v21, v10, v10
	v_add_f32_e32 v20, v21, v20
	v_mul_f32_e32 v21, v7, v7
	v_fmac_f32_e32 v21, v11, v11
	v_add_f32_e32 v20, v21, v20
	s_waitcnt lgkmcnt(1)
	v_mul_f32_e32 v21, v12, v12
	s_waitcnt lgkmcnt(0)
	v_fmac_f32_e32 v21, v16, v16
	v_add_f32_e32 v20, v21, v20
	v_mul_f32_e32 v21, v13, v13
	v_fmac_f32_e32 v21, v17, v17
	v_add_f32_e32 v20, v21, v20
	v_mul_f32_e32 v21, v14, v14
	v_fmac_f32_e32 v21, v18, v18
	v_add_f32_e32 v20, v21, v20
	v_mul_f32_e32 v21, v15, v15
	v_fmac_f32_e32 v21, v19, v19
	v_add_f32_e32 v36, v21, v20
	v_or_b32_e32 v20, 0x210, v30
	v_xad_u32 v20, v20, v28, v29
	ds_read_b128 v[20:23], v20
	ds_read_b128 v[24:27], v32 offset:512
	v_or_b32_e32 v30, 0x310, v30
	v_xad_u32 v28, v30, v28, v29
	ds_read_b128 v[28:31], v28
	ds_read_b128 v[32:35], v32 offset:768
	s_waitcnt lgkmcnt(3)
	v_mul_f32_e32 v37, v20, v20
	s_waitcnt lgkmcnt(2)
	v_fmac_f32_e32 v37, v24, v24
	v_add_f32_e32 v36, v37, v36
	v_mul_f32_e32 v37, v21, v21
	v_fmac_f32_e32 v37, v25, v25
	v_add_f32_e32 v38, v37, v36
	v_pk_mul_f32 v[36:37], v[22:23], v[22:23]
	s_nop 0
	v_pk_fma_f32 v[36:37], v[26:27], v[26:27], v[36:37]
	s_nop 0
	v_add_f32_e32 v36, v36, v38
	s_waitcnt lgkmcnt(1)
	v_pk_mul_f32 v[38:39], v[28:29], v[28:29]
	v_add_f32_e32 v40, v37, v36
	s_waitcnt lgkmcnt(0)
	v_pk_fma_f32 v[38:39], v[32:33], v[32:33], v[38:39]
	v_pk_mul_f32 v[36:37], v[30:31], v[30:31]
	v_add_f32_e32 v38, v38, v40
	v_pk_fma_f32 v[36:37], v[34:35], v[34:35], v[36:37]
	v_add_f32_e32 v38, v39, v38
	v_add_f32_e32 v36, v36, v38
	v_add_f32_e32 v36, v37, v36
	ds_bpermute_b32 v37, v169, v36
	s_waitcnt lgkmcnt(0)
	v_add_f32_e32 v36, v36, v37
	ds_bpermute_b32 v37, v168, v36
	s_waitcnt lgkmcnt(0)
	v_add_f32_e32 v36, v36, v37
	ds_bpermute_b32 v37, v167, v36
	s_waitcnt lgkmcnt(0)
	v_add_f32_e32 v36, v36, v37
	v_fmamk_f32 v36, v36, 0x3b800000, v165
	v_rsq_f32_e32 v44, v36
	v_add_u32_e32 v36, s25, v2
	v_ashrrev_i32_e32 v37, 31, v36
	v_lshlrev_b64 v[36:37], 11, v[36:37]
	v_lshl_add_u64 v[36:37], s[10:11], 0, v[36:37]
	s_mov_b32 s25, s17
	v_and_b32_e32 v2, 7, v68
	v_lshl_add_u64 v[40:41], v[36:37], 0, s[24:25]
	v_lshl_add_u32 v36, v2, 5, 0
	v_add_u32_e32 v45, 0x16400, v36
	v_lshlrev_b32_e32 v2, 4, v2
	ds_read_b128 v[36:39], v45
	v_lshl_add_u64 v[46:47], v[40:41], 0, v[2:3]
	ds_read_b128 v[40:43], v45 offset:16
	v_pk_mul_f32 v[8:9], v[8:9], v[44:45] op_sel_hi:[1,0]
	v_pk_mul_f32 v[10:11], v[10:11], v[44:45] op_sel_hi:[1,0]
	v_pk_mul_f32 v[4:5], v[4:5], v[44:45] op_sel_hi:[1,0]
	s_waitcnt lgkmcnt(1)
	v_pk_mul_f32 v[8:9], v[36:37], v[8:9]
	v_pk_mul_f32 v[10:11], v[38:39], v[10:11]
	s_waitcnt lgkmcnt(0)
; __device__ __forceinline__ unsigned pk2(float lo, float hi) { f32x2 v = {lo, hi}; bf16x2_t b = __builtin_convertvector(v, bf16x2_t); return __builtin_bit_cast(unsigned, b); }
;     template <bool BG = false>
;     __device__ __forceinline__ void run(LAS unsigned char* lds, f32x16 (&O)[NCOMP][NBLK], BgConv* bg = nullptr) const {
;     ...
;         if (tid < DH) gq[tid] = qg[tid];
;         __syncthreads();
;         bf16x8 qf[KS];
;         const float qscale = ((DH == 128) ? 0.08838834764831845f : 0.0625f) * LOG2E;
; #pragma unroll
;         for (int pass = 0; pass < NRB / 2; ++pass) {
;             u32x4 qr[4]; tile_load(qr, Q + (size_t)(64 * pass) * ldq, ldq, tid);
;             tile_store_norm<DH, NCOMP>(qr, kbuf, gq, qscale, tid);
; template <bool BG = false>
; __device__ __forceinline__ void diff_unit(Frame& F, int bh, int c, BgConv* bg = nullptr) {
;     ...
;       bf16* Y = (bf16*)F.out + (size_t)TOK * 1024 + (size_t)(b * SEQ + 64 * c + l) * 1024 + hd * 256 + (tid & 7) * 8;
; #pragma unroll
;       for (int i = 0; i < 4; ++i) { const int ch = (tid & 7) + 8 * i;
;           const f32x4 g0 = gnt[2 * ch], g1 = gnt[2 * ch + 1];
;           u32x4 w;
;           w.x = pk2(o[i][0][0] * rn * g0[0], o[i][0][1] * rn * g0[1]); w.y = pk2(o[i][0][2] * rn * g0[2], o[i][0][3] * rn * g0[3]);
;           w.z = pk2(o[i][1][0] * rn * g1[0], o[i][1][1] * rn * g1[1]); w.w = pk2(o[i][1][2] * rn * g1[2], o[i][1][3] * rn * g1[3]);
;           *(u32x4*)(Y + 64 * i) = w; } }
	v_pk_mul_f32 v[4:5], v[40:41], v[4:5]
	v_cvt_pk_bf16_f32 v8, v8, v9
	v_cvt_pk_bf16_f32 v9, v10, v11
	v_cvt_pk_bf16_f32 v10, v4, v5
	v_pk_mul_f32 v[4:5], v[6:7], v[44:45] op_sel_hi:[1,0]
	v_pk_mul_f32 v[16:17], v[16:17], v[44:45] op_sel_hi:[1,0]
	v_pk_mul_f32 v[36:37], v[42:43], v[4:5]
	ds_read_b128 v[4:7], v45 offset:256
	v_cvt_pk_bf16_f32 v11, v36, v37
	global_store_dwordx4 v[46:47], v[8:11], off
	ds_read_b128 v[8:11], v45 offset:272
	s_waitcnt lgkmcnt(1)
	v_pk_mul_f32 v[4:5], v[4:5], v[16:17]
	v_pk_mul_f32 v[16:17], v[18:19], v[44:45] op_sel_hi:[1,0]
	v_cvt_pk_bf16_f32 v4, v4, v5
	v_pk_mul_f32 v[6:7], v[6:7], v[16:17]
	s_nop 0
	v_cvt_pk_bf16_f32 v5, v6, v7
	v_pk_mul_f32 v[6:7], v[12:13], v[44:45] op_sel_hi:[1,0]
	s_waitcnt lgkmcnt(0)
	v_pk_mul_f32 v[6:7], v[8:9], v[6:7]
	v_pk_mul_f32 v[8:9], v[14:15], v[44:45] op_sel_hi:[1,0]
	v_cvt_pk_bf16_f32 v6, v6, v7
	v_pk_mul_f32 v[12:13], v[10:11], v[8:9]
	ds_read_b128 v[8:11], v45 offset:512
	v_cvt_pk_bf16_f32 v7, v12, v13
	global_store_dwordx4 v[46:47], v[4:7], off offset:128
	ds_read_b128 v[4:7], v45 offset:528
	v_pk_mul_f32 v[12:13], v[24:25], v[44:45] op_sel_hi:[1,0]
	s_waitcnt lgkmcnt(1)
	v_pk_mul_f32 v[8:9], v[8:9], v[12:13]
	v_pk_mul_f32 v[12:13], v[26:27], v[44:45] op_sel_hi:[1,0]
	v_cvt_pk_bf16_f32 v8, v8, v9
	v_pk_mul_f32 v[10:11], v[10:11], v[12:13]
	s_nop 0
	v_cvt_pk_bf16_f32 v9, v10, v11
	v_pk_mul_f32 v[10:11], v[20:21], v[44:45] op_sel_hi:[1,0]
	s_waitcnt lgkmcnt(0)
	v_pk_mul_f32 v[4:5], v[4:5], v[10:11]
	s_nop 0
	v_cvt_pk_bf16_f32 v10, v4, v5
	v_pk_mul_f32 v[4:5], v[22:23], v[44:45] op_sel_hi:[1,0]
	s_nop 0
	v_pk_mul_f32 v[12:13], v[6:7], v[4:5]
	ds_read_b128 v[4:7], v45 offset:768
	v_cvt_pk_bf16_f32 v11, v12, v13
	global_store_dwordx4 v[46:47], v[8:11], off offset:256
	ds_read_b128 v[8:11], v45 offset:784
	v_pk_mul_f32 v[12:13], v[32:33], v[44:45] op_sel_hi:[1,0]
	s_waitcnt lgkmcnt(1)
	v_pk_mul_f32 v[4:5], v[4:5], v[12:13]
	v_pk_mul_f32 v[12:13], v[34:35], v[44:45] op_sel_hi:[1,0]
	v_cvt_pk_bf16_f32 v4, v4, v5
	v_pk_mul_f32 v[6:7], v[6:7], v[12:13]
	s_nop 0
	v_cvt_pk_bf16_f32 v5, v6, v7
	v_pk_mul_f32 v[6:7], v[28:29], v[44:45] op_sel_hi:[1,0]
	s_waitcnt lgkmcnt(0)
	v_pk_mul_f32 v[6:7], v[8:9], v[6:7]
	v_pk_mul_f32 v[8:9], v[30:31], v[44:45] op_sel_hi:[1,0]
	v_cvt_pk_bf16_f32 v6, v6, v7
	v_pk_mul_f32 v[8:9], v[10:11], v[8:9]
	s_nop 0
	v_cvt_pk_bf16_f32 v7, v8, v9
	global_store_dwordx4 v[46:47], v[4:7], off offset:384
	s_barrier
	global_load_dword v172, v3, s[8:9]
	v_mov_b32_e32 v4, v0
	s_nop 0
	v_readfirstlane_b32 s79, v4
	v_cmp_gt_i32_e32 vcc, s42, v4
	s_and_saveexec_b64 s[36:37], vcc
	s_cbranch_execz .LBB0_753
.LBB0_753:
	s_or_b64 exec, exec, s[36:37]
	s_lshl_b32 s16, s73, 6
	s_or_b32 s25, s76, s16
	s_mul_i32 s36, s25, 0x3c00
	s_mul_hi_i32 s16, s25, 0x3c00
	s_add_u32 s36, s3, s36
	s_addc_u32 s16, s12, s16
	s_add_u32 s36, s36, s24
	v_ashrrev_i32_e32 v176, 3, v4
	v_lshlrev_b32_e32 v2, 3, v4
	s_addc_u32 s37, s16, 0
	v_and_b32_e32 v2, 56, v2
	v_mad_i64_i32 v[8:9], s[84:85], v176, s46, 0
	v_lshl_add_u64 v[6:7], v[8:9], 1, s[36:37]
	v_lshlrev_b32_e32 v2, 1, v2
	v_lshl_add_u64 v[6:7], v[6:7], 0, v[2:3]
	v_add_co_u32_e32 v10, vcc, s47, v6
	v_lshl_add_u64 v[30:31], v[6:7], 0, s[20:21]
	s_nop 0
	v_addc_co_u32_e32 v11, vcc, 0, v7, vcc
	s_waitcnt lgkmcnt(0)
	s_barrier
	global_load_dwordx4 v[10:13], v[10:11], off offset:2048
	v_ashrrev_i32_e32 v7, 2, v4
	global_load_dwordx4 v[14:17], v[30:31], off offset:128
	v_and_b32_e32 v5, 7, v4
	v_and_b32_e32 v18, 0xffffffe, v7
	v_lshl_add_u32 v58, v5, 5, s77
	v_lshlrev_b32_e32 v6, 4, v5
	v_or_b32_e32 v5, 8, v5
	v_mul_lo_u32 v26, v18, s45
	v_lshl_add_u32 v59, v5, 5, s77
	v_lshlrev_b32_e32 v60, 4, v5
	ds_read_b128 v[18:21], v58
	ds_read_b128 v[22:25], v58 offset:16
	v_add_u32_e32 v5, 0, v26
	global_load_dwordx4 v[26:29], v[30:31], off offset:256
	s_nop 0
	global_load_dwordx4 v[30:33], v[30:31], off offset:384
	v_or_b32_e32 v7, 1, v7
	v_mul_lo_u32 v7, v7, s45
	v_add_u32_e32 v7, 0, v7
	s_ashr_i32 s16, s79, 6
	s_ashr_i32 s36, s79, 7
	s_lshr_b32 s37, s79, 31
	s_add_i32 s37, s36, s37
	s_lshr_b32 s76, s16, 30
	s_and_b32 s37, s37, -2
	s_add_i32 s76, s16, s76
	s_sub_i32 s36, s36, s37
	s_ashr_i32 s37, s76, 2
	v_bfe_u32 v179, v4, 5, 1
	s_add_i32 s77, s37, 1
	s_lshl_b32 s76, s37, 5
	v_and_b32_e32 v171, 31, v4
	s_cmp_gt_u32 s77, 2
	v_lshlrev_b32_e32 v173, 4, v179
	s_waitcnt vmcnt(3)
	v_lshlrev_b32_e32 v34, 16, v13
	v_and_b32_e32 v35, 0xffff0000, v13
	v_and_b32_e32 v37, 0xffff0000, v12
	v_and_b32_e32 v13, 0xffff0000, v11
	v_and_b32_e32 v39, 0xffff0000, v10
	s_waitcnt vmcnt(2)
	v_and_b32_e32 v41, 0xffff0000, v17
	v_and_b32_e32 v43, 0xffff0000, v16
	v_and_b32_e32 v45, 0xffff0000, v15
	v_and_b32_e32 v47, 0xffff0000, v14
	v_lshlrev_b32_e32 v36, 16, v12
	v_lshlrev_b32_e32 v12, 16, v11
	v_lshlrev_b32_e32 v38, 16, v10
	v_lshlrev_b32_e32 v40, 16, v17
	v_lshlrev_b32_e32 v42, 16, v16
	v_lshlrev_b32_e32 v44, 16, v15
	v_lshlrev_b32_e32 v46, 16, v14
	v_mov_b32_e32 v14, v35
	v_mov_b32_e32 v15, v41
	v_mov_b32_e32 v48, v37
	v_mov_b32_e32 v49, v43
	v_mov_b32_e32 v52, v13
	v_mov_b32_e32 v53, v45
	v_mov_b32_e32 v56, v39
	v_mov_b32_e32 v57, v47
	v_mov_b32_e32 v10, v34
	v_mov_b32_e32 v11, v40
	v_mov_b32_e32 v16, v36
	v_mov_b32_e32 v17, v42
	v_mov_b32_e32 v50, v12
	v_mov_b32_e32 v51, v44
	v_mov_b32_e32 v54, v38
	v_mov_b32_e32 v55, v46
	v_pk_mul_f32 v[14:15], v[14:15], v[14:15]
	v_pk_mul_f32 v[48:49], v[48:49], v[48:49]
	v_pk_mul_f32 v[52:53], v[52:53], v[52:53]
	v_pk_mul_f32 v[56:57], v[56:57], v[56:57]
	v_pk_fma_f32 v[10:11], v[10:11], v[10:11], v[14:15]
	v_pk_fma_f32 v[14:15], v[16:17], v[16:17], v[48:49]
	v_pk_fma_f32 v[16:17], v[50:51], v[50:51], v[52:53]
	v_pk_fma_f32 v[48:49], v[54:55], v[54:55], v[56:57]
	v_add_u32_e32 v54, v5, v60
	v_pk_add_f32 v[16:17], v[48:49], v[16:17]
	v_add_u32_e32 v49, v5, v6
	v_pk_add_f32 v[14:15], v[14:15], v[16:17]
	v_add_u32_e32 v55, v7, v6
	v_pk_add_f32 v[10:11], v[10:11], v[14:15]
	v_add_u32_e32 v56, v7, v60
	v_add_f32_e32 v10, v10, v11
	ds_bpermute_b32 v11, v169, v10
	s_waitcnt lgkmcnt(0)
; template <int DH, int NCOMP>
; __device__ __forceinline__ void tile_store_norm(const u32x4 (&r)[4], LAS unsigned char* buf, const LAS float* gain, float scale, int tid) {
;     ...
;     for (int i = 0; i < 4; ++i) { const int c = (NCOMP == 2) ? (i >> 1) : 0;
;         const float a0 = bflo(r[i].x), a1 = bfhi(r[i].x), a2 = bflo(r[i].y), a3 = bfhi(r[i].y), a4 = bflo(r[i].z), a5 = bfhi(r[i].z), a6 = bflo(r[i].w), a7 = bfhi(r[i].w);
;         ss[c] += (a0 * a0 + a1 * a1) + (a2 * a2 + a3 * a3) + (a4 * a4 + a5 * a5) + (a6 * a6 + a7 * a7); }
; #pragma unroll
;     for (int c = 0; c < NCOMP; ++c) { ss[c] += __shfl_xor(ss[c], 1); ss[c] += __shfl_xor(ss[c], 2); ss[c] += __shfl_xor(ss[c], 4); ss[c] = frsq(ss[c] * (1.0f / DH) + NORM_EPS) * scale; }
; #pragma unroll
;     for (int i = 0; i < 4; ++i) { const int c = (NCOMP == 2) ? (i >> 1) : 0; const int chunk = (tid & 7) + 8 * i, dch = chunk % CPR; const float rn = ss[c];
;         const f32x4 g0 = *(const LAS f32x4*)(gain + dch * 8), g1 = *(const LAS f32x4*)(gain + dch * 8 + 4);
;         u32x4 w;
;         w.x = pk2(bflo(r[i].x) * rn * g0[0], bfhi(r[i].x) * rn * g0[1]); w.y = pk2(bflo(r[i].y) * rn * g0[2], bfhi(r[i].y) * rn * g0[3]);
;         w.z = pk2(bflo(r[i].z) * rn * g1[0], bfhi(r[i].z) * rn * g1[1]); w.w = pk2(bflo(r[i].w) * rn * g1[2], bfhi(r[i].w) * rn * g1[3]);
;         *(LAS u32x4*)(buf + ((tid >> 3) * NCOMP + c) * KST + dch * 16) = w; }
; }
; template <int DH, int NCOMP>
; __device__ __forceinline__ void tile_store_k(const u32x4 (&r)[4], LAS unsigned char* buf, int tid) {
;     constexpr int KST = DH * 2 + 16, CPR = DH / 8;
; #pragma unroll
;     for (int i = 0; i < 4; ++i) { const int c = (NCOMP == 2) ? (i >> 1) : 0; const int chunk = (tid & 7) + 8 * i, dch = chunk % CPR;
;         *(LAS u32x4*)(buf + ((tid >> 3) * NCOMP + c) * KST + dch * 16) = r[i]; }
; }
;     template <bool BG = false>
;     __device__ __forceinline__ void run(LAS unsigned char* lds, f32x16 (&O)[NCOMP][NBLK], BgConv* bg = nullptr) const {
;         int tid = threadIdx.x; asm volatile("" : "+v"(tid));
;         const int lane = tid & 63, wid = __builtin_amdgcn_readfirstlane(tid >> 6), r = lane & 31, h = lane >> 5;
;         const int kh = wid & 1, compA = (wid >> 1) % NCOMP, rbA = wid / (2 * NCOMP);
;         const int dvp = wid % NDV, rbB = wid / NDV;
;         const int b16 = (lane >> 4) & 1, q4 = (lane & 15) >> 2, p4 = lane & 3;
	v_add_f32_e32 v10, v10, v11
	ds_bpermute_b32 v11, v168, v10
	s_waitcnt lgkmcnt(0)
	v_add_f32_e32 v10, v10, v11
	ds_bpermute_b32 v11, v167, v10
	s_waitcnt lgkmcnt(0)
	v_add_f32_e32 v10, v10, v11
	v_fmamk_f32 v10, v10, 0x3c000000, v165
	v_rsq_f32_e32 v10, v10
	s_nop 0
	v_mul_f32_e32 v48, 0x3e0293ee, v10
	v_pk_mul_f32 v[12:13], v[48:49], v[12:13] op_sel_hi:[0,1]
	v_pk_mul_f32 v[16:17], v[48:49], v[34:35] op_sel_hi:[0,1]
	v_pk_mul_f32 v[14:15], v[48:49], v[36:37] op_sel_hi:[0,1]
	v_pk_mul_f32 v[12:13], v[20:21], v[12:13]
	v_pk_mul_f32 v[16:17], v[24:25], v[16:17]
	s_waitcnt vmcnt(1)
	v_and_b32_e32 v21, 0xffff0000, v29
	v_lshlrev_b32_e32 v24, 16, v27
	v_and_b32_e32 v25, 0xffff0000, v27
	s_waitcnt vmcnt(0)
	v_and_b32_e32 v27, 0xffff0000, v33
	v_pk_mul_f32 v[14:15], v[22:23], v[14:15]
	v_lshlrev_b32_e32 v20, 16, v29
	v_lshlrev_b32_e32 v22, 16, v28
	v_and_b32_e32 v23, 0xffff0000, v28
	v_lshlrev_b32_e32 v28, 16, v26
	v_and_b32_e32 v29, 0xffff0000, v26
	v_lshlrev_b32_e32 v26, 16, v33
	v_mov_b32_e32 v36, v21
	v_mov_b32_e32 v37, v27
	v_mov_b32_e32 v34, v20
	v_mov_b32_e32 v35, v26
	v_pk_mul_f32 v[36:37], v[36:37], v[36:37]
	v_pk_mul_f32 v[10:11], v[48:49], v[38:39] op_sel_hi:[0,1]
	v_pk_fma_f32 v[34:35], v[34:35], v[34:35], v[36:37]
	v_and_b32_e32 v37, 0xffff0000, v32
	v_lshlrev_b32_e32 v36, 16, v32
	v_mov_b32_e32 v38, v23
	v_mov_b32_e32 v39, v37
	v_mov_b32_e32 v32, v22
	v_mov_b32_e32 v33, v36
	v_pk_mul_f32 v[38:39], v[38:39], v[38:39]
	v_mov_b32_e32 v50, v25
	v_pk_fma_f32 v[32:33], v[32:33], v[32:33], v[38:39]
	v_and_b32_e32 v39, 0xffff0000, v31
	v_lshlrev_b32_e32 v38, 16, v31
	v_mov_b32_e32 v51, v39
	v_pk_mul_f32 v[10:11], v[18:19], v[10:11]
	v_pk_mul_f32 v[18:19], v[48:49], v[46:47] op_sel_hi:[0,1]
	v_mov_b32_e32 v46, v24
	v_mov_b32_e32 v47, v38
	v_pk_mul_f32 v[50:51], v[50:51], v[50:51]
	v_mov_b32_e32 v52, v29
	v_pk_fma_f32 v[46:47], v[46:47], v[46:47], v[50:51]
	v_and_b32_e32 v51, 0xffff0000, v30
	v_lshlrev_b32_e32 v50, 16, v30
	v_mov_b32_e32 v53, v51
	v_mov_b32_e32 v30, v28
	v_mov_b32_e32 v31, v50
	v_pk_mul_f32 v[52:53], v[52:53], v[52:53]
	v_cvt_pk_bf16_f32 v10, v10, v11
	v_pk_fma_f32 v[30:31], v[30:31], v[30:31], v[52:53]
	v_cvt_pk_bf16_f32 v11, v12, v13
	v_pk_add_f32 v[30:31], v[30:31], v[46:47]
	v_cvt_pk_bf16_f32 v12, v14, v15
	v_pk_add_f32 v[30:31], v[32:33], v[30:31]
	v_cvt_pk_bf16_f32 v13, v16, v17
	v_pk_add_f32 v[30:31], v[34:35], v[30:31]
	ds_write_b128 v49, v[10:13]
	v_add_f32_e32 v30, v30, v31
	ds_read_b128 v[10:13], v59
	ds_read_b128 v[14:17], v59 offset:16
	ds_bpermute_b32 v31, v169, v30
	s_waitcnt lgkmcnt(2)
	v_pk_mul_f32 v[10:11], v[10:11], v[18:19]
	v_pk_mul_f32 v[18:19], v[48:49], v[44:45] op_sel_hi:[0,1]
	v_pk_mul_f32 v[12:13], v[12:13], v[18:19]
	s_waitcnt lgkmcnt(0)
	v_add_f32_e32 v18, v30, v31
	ds_bpermute_b32 v19, v168, v18
	v_cvt_pk_bf16_f32 v10, v10, v11
	v_cvt_pk_bf16_f32 v11, v12, v13
	v_pk_mul_f32 v[12:13], v[48:49], v[42:43] op_sel_hi:[0,1]
	v_pk_mul_f32 v[12:13], v[14:15], v[12:13]
	s_waitcnt lgkmcnt(0)
	v_add_f32_e32 v18, v18, v19
	ds_bpermute_b32 v19, v167, v18
	v_pk_mul_f32 v[14:15], v[48:49], v[40:41] op_sel_hi:[0,1]
	v_pk_mul_f32 v[14:15], v[16:17], v[14:15]
	v_cvt_pk_bf16_f32 v12, v12, v13
	v_cvt_pk_bf16_f32 v13, v14, v15
	ds_write_b128 v54, v[10:13]
	s_waitcnt lgkmcnt(1)
	v_add_f32_e32 v10, v18, v19
	v_fmamk_f32 v10, v10, 0x3c000000, v165
	v_rsq_f32_e32 v18, v10
	ds_read_b128 v[10:13], v58
	ds_read_b128 v[14:17], v58 offset:16
	v_mul_f32_e32 v18, 0x3e0293ee, v18
	v_pk_mul_f32 v[28:29], v[18:19], v[28:29] op_sel_hi:[0,1]
	v_pk_mul_f32 v[24:25], v[18:19], v[24:25] op_sel_hi:[0,1]
	s_waitcnt lgkmcnt(1)
	v_pk_mul_f32 v[10:11], v[10:11], v[28:29]
	v_pk_mul_f32 v[12:13], v[12:13], v[24:25]
	v_cvt_pk_bf16_f32 v10, v10, v11
	v_cvt_pk_bf16_f32 v11, v12, v13
	v_pk_mul_f32 v[12:13], v[18:19], v[22:23] op_sel_hi:[0,1]
	s_waitcnt lgkmcnt(0)
	v_pk_mul_f32 v[12:13], v[14:15], v[12:13]
	v_pk_mul_f32 v[14:15], v[18:19], v[20:21] op_sel_hi:[0,1]
	v_pk_mul_f32 v[14:15], v[16:17], v[14:15]
	v_cvt_pk_bf16_f32 v12, v12, v13
	v_cvt_pk_bf16_f32 v13, v14, v15
	ds_write_b128 v55, v[10:13]
	ds_read_b128 v[10:13], v59
	ds_read_b128 v[14:17], v59 offset:16
	v_pk_mul_f32 v[20:21], v[18:19], v[50:51] op_sel_hi:[0,1]
	s_waitcnt lgkmcnt(1)
	v_pk_mul_f32 v[10:11], v[10:11], v[20:21]
	v_pk_mul_f32 v[20:21], v[18:19], v[38:39] op_sel_hi:[0,1]
	v_pk_mul_f32 v[12:13], v[12:13], v[20:21]
	v_cvt_pk_bf16_f32 v10, v10, v11
	v_cvt_pk_bf16_f32 v11, v12, v13
	v_pk_mul_f32 v[12:13], v[18:19], v[36:37] op_sel_hi:[0,1]
	s_waitcnt lgkmcnt(0)
	v_pk_mul_f32 v[12:13], v[12:13], v[14:15]
	v_pk_mul_f32 v[14:15], v[18:19], v[26:27] op_sel_hi:[0,1]
	v_pk_mul_f32 v[14:15], v[14:15], v[16:17]
	v_cvt_pk_bf16_f32 v12, v12, v13
	v_cvt_pk_bf16_f32 v13, v14, v15
	ds_write_b128 v56, v[10:13]
	s_waitcnt lgkmcnt(0)
	s_barrier
	s_cbranch_scc1 .LBB0_755
	v_and_or_b32 v10, s76, 32, v171
	v_lshl_add_u32 v10, v10, 1, s36
	v_mul_i32_i24_e32 v10, 0x110, v10
	v_add3_u32 v10, 0, v10, v173
	ds_read_b128 v[112:115], v10
	ds_read_b128 v[108:111], v10 offset:32
	ds_read_b128 v[104:107], v10 offset:64
	ds_read_b128 v[100:103], v10 offset:96
	ds_read_b128 v[96:99], v10 offset:128
	ds_read_b128 v[92:95], v10 offset:160
	ds_read_b128 v[88:91], v10 offset:192
	ds_read_b128 v[84:87], v10 offset:224

; #define LAS __attribute__((address_space(3)))
; template <bool BG = false>
; __device__ __forceinline__ void diff_unit(Frame& F, int bh, int c, BgConv* bg = nullptr) {
;     ...
;     if (tid < 256) ((LAS float*)(lds + AT_G + 1024))[tid] = F.in[14][tid] * (1.0f - LAM_INIT);
.LBB0_777:
	s_or_b64 exec, exec, s[26:27]
	s_waitcnt lgkmcnt(0)
	v_mov_b32_e32 v68, v0
	s_barrier
	global_load_dword v2, v3, s[4:5]
	v_cmp_gt_i32_e32 vcc, s67, v68
	s_and_saveexec_b64 s[26:27], vcc
	s_cbranch_execz .LBB0_722
	s_branch .LBB0_722

; #define LAS __attribute__((address_space(3)))
; __device__ __forceinline__ void gla_out_unit(Frame& F, int bh, int n) {
;     ...
;     const bf16* zrow = WSP(bf16, WS_Z) + (size_t)(b * SEQ + 64 * n) * NZ;
;     LAS unsigned char* lds = F.lds;
;     const bf16* sb = WSP(bf16, WS_SB) + (size_t)(bh * 64 + n) * 256 * 128 + (size_t)(32 * wid + r) * 128 + 8 * h;
;     bf16x8 sf[8];
; #pragma unroll
;     for (int s = 0; s < 8; ++s) sf[s] = *(const bf16x8*)(sb + 16 * s);
;     gla_load_la(lds, zrow + ZA_GLA + hd * 128, tid);
;     u32x4 qr[2], kr[2];
;     { const bf16* p = zrow + ZQ_GLA + hd * 128 + (size_t)(tid >> 3) * NZ + (tid & 7) * 8; qr[0] = *(const u32x4*)p; qr[1] = *(const u32x4*)(p + 64); }
;     { const bf16* p = zrow + ZK_GLA + hd * 128 + (size_t)(tid >> 3) * NZ + (tid & 7) * 8; kr[0] = *(const u32x4*)p; kr[1] = *(const u32x4*)(p + 64); }
;     { u32x4 vr[4]; tile_load(vr, zrow + ZV_GLA + hd * 256, NZ, tid); tile_store_raw(vr, lds + GL_VT, tid); }
;     u32x4 gr[4]; tile_load(gr, zrow + ZG_GLA + hd * 256, NZ, tid);
;     if (tid < 256) ((LAS float*)(lds + GL_RED))[tid] = F.in[7][tid];
.LBB0_797:
	s_ashr_i32 s20, s82, 6
	v_and_b32_e32 v251, 0xff, v0
	v_lshlrev_b32_e32 v251, 2, v251
	global_load_dword v250, v251, s[30:31]
	s_lshl_b32 s4, s20, 10
	s_and_b32 s4, s4, 0xfffff000
	s_and_b32 s21, s15, 0xfc0
	s_or_b32 s4, s4, s21
	s_mul_i32 s38, s4, 0x3c00
	s_and_b32 s39, s20, 3
	v_mov_b32_e32 v84, v0
	s_mul_hi_i32 s21, s4, 0x3c00
	s_add_u32 s42, s12, s38
	s_addc_u32 s43, s13, s21
	v_and_b32_e32 v92, 31, v84
	s_lshl_b32 s38, s39, 8
	v_or_b32_e32 v82, s3, v92
	s_add_u32 s20, s42, s38
	v_lshlrev_b64 v[2:3], 8, v[82:83]
	v_lshrrev_b32_e32 v4, 1, v84
	s_addc_u32 s21, s43, 0
	v_and_or_b32 v2, v4, 16, v2
	s_add_u32 s40, s20, 0x3800
	v_lshl_add_u64 v[2:3], s[8:9], 0, v[2:3]
	s_addc_u32 s41, s21, 0
	global_load_dwordx4 v[78:81], v[2:3], off
	global_load_dwordx4 v[74:77], v[2:3], off offset:32
	global_load_dwordx4 v[70:73], v[2:3], off offset:64
	global_load_dwordx4 v[66:69], v[2:3], off offset:96
	global_load_dwordx4 v[62:65], v[2:3], off offset:128
	global_load_dwordx4 v[58:61], v[2:3], off offset:160
	global_load_dwordx4 v[54:57], v[2:3], off offset:192
	global_load_dwordx4 v[50:53], v[2:3], off offset:224
	v_ashrrev_i32_e32 v90, 3, v84
	v_mov_b64_e32 v[2:3], s[40:41]
	v_and_b32_e32 v22, 7, v84
	v_mad_i64_i32 v[2:3], s[40:41], v90, s25, v[2:3]
	v_lshlrev_b32_e32 v18, 4, v22
	v_mov_b32_e32 v19, v83
	v_lshl_add_u64 v[2:3], v[2:3], 0, v[18:19]
	global_load_dwordx4 v[24:27], v[2:3], off
	global_load_dwordx4 v[28:31], v[2:3], off offset:128
	v_mov_b64_e32 v[2:3], s[20:21]
	v_mad_i64_i32 v[2:3], s[20:21], v90, s25, v[2:3]
	s_lshl_b32 s20, s39, 9
	s_add_u32 s20, s42, s20
	s_addc_u32 s21, s43, 0
	v_lshl_add_u64 v[2:3], v[2:3], 0, v[18:19]
	v_mov_b64_e32 v[20:21], s[20:21]
	v_lshlrev_b32_e32 v19, 4, v84
	v_mad_i64_i32 v[20:21], s[20:21], v90, s25, v[20:21]
	v_and_b32_e32 v32, 0x70, v19
	v_mov_b32_e32 v33, v83
	v_lshl_add_u64 v[20:21], v[20:21], 0, v[32:33]
	global_load_dwordx4 v[14:17], v[2:3], off
	global_load_dwordx4 v[6:9], v[2:3], off offset:128
	global_load_dwordx4 v[10:13], v[2:3], off offset:1024
	s_nop 0
	global_load_dwordx4 v[2:5], v[2:3], off offset:1152
	s_nop 0
	global_load_dwordx4 v[94:97], v[20:21], off offset:2048
	global_load_dwordx4 v[98:101], v[20:21], off offset:2176
	global_load_dwordx4 v[102:105], v[20:21], off offset:2304
	global_load_dwordx4 v[106:109], v[20:21], off offset:2432
	v_lshl_add_u64 v[34:35], v[20:21], 0, s[16:17]
	v_add_co_u32_e32 v20, vcc, 0x1000, v20
	v_lshl_add_u32 v19, v90, 9, 0
	s_nop 0
	v_addc_co_u32_e32 v21, vcc, 0, v21, vcc
	global_load_dwordx4 v[42:45], v[34:35], off offset:128
	global_load_dwordx4 v[38:41], v[34:35], off offset:256
	global_load_dwordx4 v[46:49], v[20:21], off
	s_nop 0
	global_load_dwordx4 v[34:37], v[34:35], off offset:384
	v_lshlrev_b32_e32 v91, 5, v22
	v_add_u32_e32 v20, v19, v91
	v_cmp_gt_i32_e32 vcc, s26, v84
	s_waitcnt vmcnt(13)
	v_lshlrev_b32_e32 v110, 16, v24
	v_and_b32_e32 v111, 0xffff0000, v24
	v_lshlrev_b32_e32 v112, 16, v25
	v_and_b32_e32 v113, 0xffff0000, v25
	v_lshlrev_b32_e32 v24, 16, v26
	v_and_b32_e32 v25, 0xffff0000, v26
	v_lshlrev_b32_e32 v26, 16, v27
	v_and_b32_e32 v27, 0xffff0000, v27
	s_waitcnt vmcnt(12)
	v_lshlrev_b32_e32 v114, 16, v28
	v_and_b32_e32 v115, 0xffff0000, v28
	v_lshlrev_b32_e32 v116, 16, v29
	v_and_b32_e32 v117, 0xffff0000, v29
	v_lshlrev_b32_e32 v28, 16, v30
	v_and_b32_e32 v29, 0xffff0000, v30
	v_lshlrev_b32_e32 v30, 16, v31
	v_and_b32_e32 v31, 0xffff0000, v31
	ds_write_b128 v20, v[110:113]
	ds_write_b128 v20, v[24:27] offset:16
	ds_write_b128 v20, v[114:117] offset:256
	ds_write_b128 v20, v[28:31] offset:272
	v_lshlrev_b32_e32 v20, 6, v90
	v_add3_u32 v20, v19, v20, v32
	s_waitcnt vmcnt(7)
	ds_write_b128 v20, v[94:97] offset:32768
	s_waitcnt vmcnt(6)
	ds_write_b128 v20, v[98:101] offset:32896
	s_waitcnt vmcnt(5)
	ds_write_b128 v20, v[102:105] offset:33024
	s_waitcnt vmcnt(4)
	ds_write_b128 v20, v[106:109] offset:33152
	s_and_saveexec_b64 s[20:21], vcc
	s_cbranch_execz .LBB0_799
	v_ashrrev_i32_e32 v85, 31, v84
	v_lshl_add_u32 v21, v84, 2, 0
	v_add_u32_e32 v21, 0x1c800, v21
	ds_write_b32 v21, v250
